# stack10 + P7 output section: second-half silu-gate loads issued with the first half's; grid-barrier census taken under the P1 counter wait
# baseline (speedup 1.0000x reference)
.LBB0_106:
	s_add_u32 s62, s18, 0x4000000
	s_addc_u32 s63, s19, 0
	s_cmp_lt_i32 s54, 2
	v_writelane_b32 v255, s48, 8
	s_cselect_b64 s[10:11], -1, 0
	s_cmp_gt_i32 s54, 1
	v_writelane_b32 v255, s49, 9
	s_cselect_b64 s[0:1], -1, 0
	s_cmp_lt_i32 s23, 2
	s_cselect_b64 s[2:3], -1, 0
	v_writelane_b32 v255, s64, 10
	s_or_b64 s[0:1], s[0:1], s[2:3]
	v_writelane_b32 v255, s50, 11
	s_and_b64 vcc, exec, s[0:1]
	s_nop 0
	v_writelane_b32 v255, s51, 12
	s_cbranch_vccnz .LBB0_119
	s_and_saveexec_b64 s[4:5], s[96:97]
	s_cbranch_execz .LBB0_115
	v_mov_b32_e32 v30, 0
	v_mov_b32_e32 v29, 0x1000
	global_load_dword v31, v30, s[26:27] offset:1024 sc1
	global_load_dword v32, v30, s[26:27] offset:1280 sc1
	global_load_dword v33, v30, s[26:27] offset:1536 sc1
	global_load_dword v34, v30, s[26:27] offset:1792 sc1
	global_load_dword v35, v30, s[26:27] offset:2048 sc1
	global_load_dword v36, v30, s[26:27] offset:2304 sc1
	global_load_dword v37, v30, s[26:27] offset:2560 sc1
	global_load_dword v38, v30, s[26:27] offset:2816 sc1
	global_load_dword v39, v30, s[26:27] offset:3072 sc1
	global_load_dword v40, v30, s[26:27] offset:3328 sc1
	global_load_dword v41, v30, s[26:27] offset:3584 sc1
	global_load_dword v42, v30, s[26:27] offset:3840 sc1
	global_load_dword v43, v29, s[26:27] offset:0 sc1
	global_load_dword v44, v29, s[26:27] offset:256 sc1
	global_load_dword v45, v29, s[26:27] offset:512 sc1
	global_load_dword v46, v29, s[26:27] offset:768 sc1
	s_getreg_b32 s98, hwreg(HW_REG_XCC_ID, 0, 4)
	s_mov_b32 s99, 0
	s_mov_b32 s100, 0
	s_mov_b32 s101, 0
	s_waitcnt vmcnt(0)
	v_readfirstlane_b32 vcc_lo, v31
	s_nop 0
	s_add_u32 s99, s99, vcc_lo
	s_cmp_lg_u32 vcc_lo, 0
	s_addc_u32 s100, s100, 0
	s_cmp_eq_u32 s98, 0
	s_cselect_b32 s101, vcc_lo, s101
	v_readfirstlane_b32 vcc_lo, v32
	s_nop 0
	s_add_u32 s99, s99, vcc_lo
	s_cmp_lg_u32 vcc_lo, 0
	s_addc_u32 s100, s100, 0
	s_cmp_eq_u32 s98, 1
	s_cselect_b32 s101, vcc_lo, s101
	v_readfirstlane_b32 vcc_lo, v33
	s_nop 0
	s_add_u32 s99, s99, vcc_lo
	s_cmp_lg_u32 vcc_lo, 0
	s_addc_u32 s100, s100, 0
	s_cmp_eq_u32 s98, 2
	s_cselect_b32 s101, vcc_lo, s101
	v_readfirstlane_b32 vcc_lo, v34
	s_nop 0
	s_add_u32 s99, s99, vcc_lo
	s_cmp_lg_u32 vcc_lo, 0
	s_addc_u32 s100, s100, 0
	s_cmp_eq_u32 s98, 3
	s_cselect_b32 s101, vcc_lo, s101
	v_readfirstlane_b32 vcc_lo, v35
	s_nop 0
	s_add_u32 s99, s99, vcc_lo
	s_cmp_lg_u32 vcc_lo, 0
	s_addc_u32 s100, s100, 0
	s_cmp_eq_u32 s98, 4
	s_cselect_b32 s101, vcc_lo, s101
	v_readfirstlane_b32 vcc_lo, v36
	s_nop 0
	s_add_u32 s99, s99, vcc_lo
	s_cmp_lg_u32 vcc_lo, 0
	s_addc_u32 s100, s100, 0
	s_cmp_eq_u32 s98, 5
	s_cselect_b32 s101, vcc_lo, s101
	v_readfirstlane_b32 vcc_lo, v37
	s_nop 0
	s_add_u32 s99, s99, vcc_lo
	s_cmp_lg_u32 vcc_lo, 0
	s_addc_u32 s100, s100, 0
	s_cmp_eq_u32 s98, 6
	s_cselect_b32 s101, vcc_lo, s101
	v_readfirstlane_b32 vcc_lo, v38
	s_nop 0
	s_add_u32 s99, s99, vcc_lo
	s_cmp_lg_u32 vcc_lo, 0
	s_addc_u32 s100, s100, 0
	s_cmp_eq_u32 s98, 7
	s_cselect_b32 s101, vcc_lo, s101
	v_readfirstlane_b32 vcc_lo, v39
	s_nop 0
	s_add_u32 s99, s99, vcc_lo
	s_cmp_lg_u32 vcc_lo, 0
	s_addc_u32 s100, s100, 0
	s_cmp_eq_u32 s98, 8
	s_cselect_b32 s101, vcc_lo, s101
	v_readfirstlane_b32 vcc_lo, v40
	s_nop 0
	s_add_u32 s99, s99, vcc_lo
	s_cmp_lg_u32 vcc_lo, 0
	s_addc_u32 s100, s100, 0
	s_cmp_eq_u32 s98, 9
	s_cselect_b32 s101, vcc_lo, s101
	v_readfirstlane_b32 vcc_lo, v41
	s_nop 0
	s_add_u32 s99, s99, vcc_lo
	s_cmp_lg_u32 vcc_lo, 0
	s_addc_u32 s100, s100, 0
	s_cmp_eq_u32 s98, 10
	s_cselect_b32 s101, vcc_lo, s101
	v_readfirstlane_b32 vcc_lo, v42
	s_nop 0
	s_add_u32 s99, s99, vcc_lo
	s_cmp_lg_u32 vcc_lo, 0
	s_addc_u32 s100, s100, 0
	s_cmp_eq_u32 s98, 11
	s_cselect_b32 s101, vcc_lo, s101
	v_readfirstlane_b32 vcc_lo, v43
	s_nop 0
	s_add_u32 s99, s99, vcc_lo
	s_cmp_lg_u32 vcc_lo, 0
	s_addc_u32 s100, s100, 0
	s_cmp_eq_u32 s98, 12
	s_cselect_b32 s101, vcc_lo, s101
	v_readfirstlane_b32 vcc_lo, v44
	s_nop 0
	s_add_u32 s99, s99, vcc_lo
	s_cmp_lg_u32 vcc_lo, 0
	s_addc_u32 s100, s100, 0
	s_cmp_eq_u32 s98, 13
	s_cselect_b32 s101, vcc_lo, s101
	v_readfirstlane_b32 vcc_lo, v45
	s_nop 0
	s_add_u32 s99, s99, vcc_lo
	s_cmp_lg_u32 vcc_lo, 0
	s_addc_u32 s100, s100, 0
	s_cmp_eq_u32 s98, 14
	s_cselect_b32 s101, vcc_lo, s101
	v_readfirstlane_b32 vcc_lo, v46
	s_nop 0
	s_add_u32 s99, s99, vcc_lo
	s_cmp_lg_u32 vcc_lo, 0
	s_addc_u32 s100, s100, 0
	s_cmp_eq_u32 s98, 15
	s_cselect_b32 s101, vcc_lo, s101
	s_cmp_lg_u32 s99, 0x100
	s_cbranch_scc1 .Lbc_skip
	s_max_u32 s101, s101, 1
	s_max_u32 s100, s100, 1
	v_mov_b32_e32 v30, 0x20020
	v_mov_b32_e32 v31, s101
	v_mov_b32_e32 v32, s100
	ds_write_b32 v30, v31
	ds_write_b32 v30, v32 offset:4
	s_waitcnt lgkmcnt(0)
.Lbc_skip:
	v_mov_b32_e32 v2, 0x16000
	s_memrealtime s[6:7]
	global_load_dword v2, v2, s[18:19] sc1
	s_add_u32 s8, s18, 0x16000
	v_readlane_b32 s0, v255, 5
	s_addc_u32 s9, s19, 0
	v_readlane_b32 s1, v255, 6
	s_movk_i32 s2, 0x80
	s_and_b64 s[0:1], s[0:1], exec
	s_cselect_b32 s0, s2, 0x100
	s_waitcnt vmcnt(0)
	v_cmp_le_u32_e32 vcc, s0, v2
	s_cbranch_vccnz .LBB0_115
	v_mov_b64_e32 v[2:3], 0x1e8481
	v_mov_b32_e32 v4, 0
	s_branch .LBB0_111

.LBB0_883:
	v_lshlrev_b32_e32 v7, 1, v228
	v_lshl_add_u32 v26, v148, 12, v7
	s_andn2_b64 vcc, exec, s[76:77]
	v_add_u32_e32 v27, 0x1000, v26
	s_cbranch_vccnz .LBB0_885
	global_load_dwordx4 v[18:21], v26, s[52:53]
	global_load_dwordx4 v[22:25], v27, s[52:53]
	v_add_u32_e32 v250, s20, v9
	v_add_u32_e32 v250, 0x80, v250
	v_lshl_add_u32 v250, v250, 12, v7
	v_add_u32_e32 v251, 0x1000, v250
	global_load_dwordx4 v[242:245], v250, s[52:53]
	global_load_dwordx4 v[246:249], v251, s[52:53]
	s_mov_b64 s[76:77], s[58:59]
	s_waitcnt vmcnt(3)
	v_mov_b32_e32 v26, v20
	s_nop 1
	v_permlane16_swap_b32_e32 v18, v26
	v_mov_b32_e32 v27, v21
	s_waitcnt vmcnt(2)
	v_mov_b32_e32 v28, v24
	v_lshlrev_b32_e32 v24, 16, v18
	v_and_b32_e32 v18, 0xffff0000, v18
	v_permlane16_swap_b32_e32 v19, v27
	v_mul_f32_e32 v24, v138, v24
	v_mul_f32_e32 v18, v139, v18
	v_permlane16_swap_b32_e32 v22, v28
	v_pk_add_f32 v[20:21], v[126:127], v[4:5]
	v_cvt_pk_bf16_f32 v18, v24, v18
	v_lshlrev_b32_e32 v24, 16, v19
	v_mov_b32_e32 v29, v25
	v_mul_f32_e32 v20, v20, v24
	v_and_b32_e32 v19, 0xffff0000, v19
	v_lshlrev_b32_e32 v24, 16, v22
	v_and_b32_e32 v22, 0xffff0000, v22
	v_permlane16_swap_b32_e32 v23, v29
	v_mul_f32_e32 v19, v21, v19
	v_mul_f32_e32 v24, v128, v24
	v_mul_f32_e32 v22, v129, v22
	v_cvt_pk_bf16_f32 v19, v20, v19
	v_pk_add_f32 v[20:21], v[88:89], v[122:123]
	v_cvt_pk_bf16_f32 v22, v24, v22
	v_lshlrev_b32_e32 v24, 16, v23
	v_and_b32_e32 v23, 0xffff0000, v23
	v_mul_f32_e32 v20, v20, v24
	v_mul_f32_e32 v21, v21, v23
	v_cvt_pk_bf16_f32 v23, v20, v21
	v_lshlrev_b32_e32 v20, 16, v26
	v_and_b32_e32 v21, 0xffff0000, v26
	v_mul_f32_e32 v20, v124, v20
	v_mul_f32_e32 v21, v125, v21
	v_pk_add_f32 v[24:25], v[84:85], v[86:87]
	v_cvt_pk_bf16_f32 v20, v20, v21
	v_lshlrev_b32_e32 v21, 16, v27
	v_mul_f32_e32 v21, v24, v21
	v_and_b32_e32 v24, 0xffff0000, v27
	v_mul_f32_e32 v24, v25, v24
	v_cvt_pk_bf16_f32 v21, v21, v24
	v_lshlrev_b32_e32 v24, 16, v28
	v_and_b32_e32 v25, 0xffff0000, v28
	v_mul_f32_e32 v24, v78, v24
	v_mul_f32_e32 v25, v79, v25
	v_pk_add_f32 v[26:27], v[80:81], v[82:83]
	v_cvt_pk_bf16_f32 v24, v24, v25
	v_lshlrev_b32_e32 v25, 16, v29
	v_mul_f32_e32 v25, v26, v25
	v_and_b32_e32 v26, 0xffff0000, v29
	v_mul_f32_e32 v26, v27, v26
	v_cvt_pk_bf16_f32 v25, v25, v26
	v_permlane16_swap_b32_e32 v18, v20
	v_permlane16_swap_b32_e32 v19, v21
	v_permlane16_swap_b32_e32 v22, v24
	v_permlane16_swap_b32_e32 v23, v25
	s_branch .LBB0_886

.LBB0_888:
	v_lshl_add_u32 v6, v13, 12, v7
	s_andn2_b64 vcc, exec, s[76:77]
	v_add_u32_e32 v7, 0x1000, v6
	s_cbranch_vccnz .LBB0_890
	s_waitcnt vmcnt(2)
	v_mov_b32_e32 v18, v242
	v_mov_b32_e32 v19, v243
	v_mov_b32_e32 v20, v244
	v_mov_b32_e32 v21, v245
	v_mov_b32_e32 v22, v246
	v_mov_b32_e32 v23, v247
	v_mov_b32_e32 v24, v248
	v_mov_b32_e32 v25, v249
	v_pk_add_f32 v[6:7], v[40:41], v[42:43]
	s_mov_b64 s[74:75], s[58:59]
	s_nop 0
	v_mov_b32_e32 v8, v20
	s_nop 1
	v_permlane16_swap_b32_e32 v18, v8
	v_mov_b32_e32 v10, v21
	v_lshlrev_b32_e32 v20, 16, v18
	v_and_b32_e32 v18, 0xffff0000, v18
	v_permlane16_swap_b32_e32 v19, v10
	s_nop 0
	v_mov_b32_e32 v12, v24
	v_mul_f32_e32 v20, v46, v20
	v_mul_f32_e32 v18, v47, v18
	v_permlane16_swap_b32_e32 v22, v12
	v_cvt_pk_bf16_f32 v18, v20, v18
	v_lshlrev_b32_e32 v20, 16, v19
	v_mov_b32_e32 v13, v25
	v_mul_f32_e32 v6, v6, v20
	v_and_b32_e32 v19, 0xffff0000, v19
	v_lshlrev_b32_e32 v20, 16, v22
	v_permlane16_swap_b32_e32 v23, v13
	v_mul_f32_e32 v7, v7, v19
	v_mul_f32_e32 v20, v44, v20
	v_and_b32_e32 v21, 0xffff0000, v22
	v_cvt_pk_bf16_f32 v19, v6, v7
	v_pk_add_f32 v[6:7], v[34:35], v[36:37]
	v_mul_f32_e32 v21, v45, v21
	v_cvt_pk_bf16_f32 v22, v20, v21
	v_lshlrev_b32_e32 v20, 16, v23
	v_mul_f32_e32 v6, v6, v20
	v_and_b32_e32 v20, 0xffff0000, v23
	v_mul_f32_e32 v7, v7, v20
	v_lshlrev_b32_e32 v20, 16, v8
	v_and_b32_e32 v8, 0xffff0000, v8
	v_mul_f32_e32 v20, v38, v20
	v_mul_f32_e32 v8, v39, v8
	v_cvt_pk_bf16_f32 v23, v6, v7
	v_pk_add_f32 v[6:7], v[30:31], v[32:33]
	v_cvt_pk_bf16_f32 v20, v20, v8
	v_lshlrev_b32_e32 v8, 16, v10
	v_mul_f32_e32 v6, v6, v8
	v_and_b32_e32 v8, 0xffff0000, v10
	v_mul_f32_e32 v7, v7, v8
	v_lshlrev_b32_e32 v8, 16, v12
	v_mul_f32_e32 v8, v26, v8
	v_and_b32_e32 v10, 0xffff0000, v12
	v_cvt_pk_bf16_f32 v21, v6, v7
	v_pk_add_f32 v[6:7], v[16:17], v[28:29]
	v_mul_f32_e32 v10, v27, v10
	v_cvt_pk_bf16_f32 v24, v8, v10
	v_lshlrev_b32_e32 v8, 16, v13
	v_mul_f32_e32 v6, v6, v8
	v_and_b32_e32 v8, 0xffff0000, v13
	v_mul_f32_e32 v7, v7, v8
	v_cvt_pk_bf16_f32 v25, v6, v7
	v_permlane16_swap_b32_e32 v18, v20
	v_permlane16_swap_b32_e32 v19, v21
	v_permlane16_swap_b32_e32 v22, v24
	v_permlane16_swap_b32_e32 v23, v25
	s_andn2_b64 vcc, exec, s[72:73]
	global_store_dwordx4 v9, v[18:21], s[74:75]
	global_store_dwordx4 v11, v[22:25], s[74:75]
	s_cbranch_vccz .LBB0_891
	s_branch .LBB0_896
